# A loop: drop canonicalising v_max pairs and no-op lgkmcnt waits
# speedup vs baseline: 1.0051x; 1.0033x over previous
; #define FLAS __attribute__((address_space(3)))
; __device__ __forceinline__ void attn_unit_a(FLAS unsigned char* lds, const Unit u) {
;     ...
;         const int vsp = (i == 0) ? 0 : ((i - 1) & 3);
;         const FLAS unsigned char* vb_ = lds + LA_V + vsp * VBUF + r32 * VPITCH + hi * 16;
;         const FLAS unsigned char* kb = lds + LA_K + ((i + 1) & 1) * KBUF;
;     ...
;         u32x4 vr[3];
; #pragma unroll
;         for (int m = 0; m < 3; ++m) vr[m] = FA_VFRAG(m);
;         const float off = cbC - mrun;
;         FA_SB();
;         float ra, rb, rm;
;         FA_PVM(0); pC0[0] = fadd_s(pC0[0], off); pC1[0] = fadd_s(pC1[0], off); pC0[1] = fadd_s(pC0[1], off); pC1[1] = fadd_s(pC1[1], off); pC0[2] = fadd_s(pC0[2], off); pC1[2] = fadd_s(pC1[2], off); FA_SB();
;         FA_PVM(1); ra = __builtin_fmaxf(__builtin_fmaxf(pC0[0], pC0[1]), pC0[2]); rb = __builtin_fmaxf(__builtin_fmaxf(pC1[0], pC1[1]), pC1[2]); pC0[3] = fadd_s(pC0[3], off); pC1[3] = fadd_s(pC1[3], off); pC0[4] = fadd_s(pC0[4], off); pC1[4] = fadd_s(pC1[4], off); FA_SB();
;         FA_PVM(2); ra = __builtin_fmaxf(__builtin_fmaxf(ra, pC0[3]), pC0[4]); rb = __builtin_fmaxf(__builtin_fmaxf(rb, pC1[3]), pC1[4]); pC0[5] = fadd_s(pC0[5], off); pC1[5] = fadd_s(pC1[5], off); pC0[6] = fadd_s(pC0[6], off); pC1[6] = fadd_s(pC1[6], off); FA_SB();
;         FA_PVM(3); ra = __builtin_fmaxf(__builtin_fmaxf(ra, pC0[5]), pC0[6]); rb = __builtin_fmaxf(__builtin_fmaxf(rb, pC1[5]), pC1[6]); pC0[7] = fadd_s(pC0[7], off); pC1[7] = fadd_s(pC1[7], off); pC0[8] = fadd_s(pC0[8], off); pC1[8] = fadd_s(pC1[8], off); FA_SB();
;         FA_PVM(4); ra = __builtin_fmaxf(__builtin_fmaxf(ra, pC0[7]), pC0[8]); rb = __builtin_fmaxf(__builtin_fmaxf(rb, pC1[7]), pC1[8]); pC0[9] = fadd_s(pC0[9], off); pC1[9] = fadd_s(pC1[9], off); pC0[10] = fadd_s(pC0[10], off); pC1[10] = fadd_s(pC1[10], off); FA_SB();
;         FA_PVM(5); ra = __builtin_fmaxf(__builtin_fmaxf(ra, pC0[9]), pC0[10]); rb = __builtin_fmaxf(__builtin_fmaxf(rb, pC1[9]), pC1[10]); pC0[11] = fadd_s(pC0[11], off); pC1[11] = fadd_s(pC1[11], off); pC0[12] = fadd_s(pC0[12], off); pC1[12] = fadd_s(pC1[12], off); FA_SB();
;         FA_PVM(6); ra = __builtin_fmaxf(__builtin_fmaxf(ra, pC0[11]), pC0[12]); rb = __builtin_fmaxf(__builtin_fmaxf(rb, pC1[11]), pC1[12]); pC0[13] = fadd_s(pC0[13], off); pC1[13] = fadd_s(pC1[13], off); pC0[14] = fadd_s(pC0[14], off); pC1[14] = fadd_s(pC1[14], off); FA_SB();
.LBB0_437:
	s_add_i32 s12, s19, -1
	s_xor_b64 s[20:21], s[24:25], -1
	s_and_b32 s18, s12, 3
	s_mulk_i32 s18, 0x4800
	s_cmp_lg_u32 s49, 0
	s_cselect_b32 s12, s18, 0
	v_add_u32_e32 v200, s12, v251
	ds_read_b128 v[96:99], v200 offset:16384
	ds_read_b128 v[100:103], v200 offset:20992
	ds_read_b128 v[108:111], v200 offset:25600
	v_sub_f32_e32 v201, v204, v211
	s_waitcnt lgkmcnt(2)
	v_mfma_f32_32x32x16_bf16 v[48:63], v[96:99], v[104:107], v[48:63]
	ds_read_b128 v[120:123], v200 offset:30208
	v_add_f32_e32 v96, v128, v201
	v_add_f32_e32 v112, v144, v201
	v_add_f32_e32 v97, v129, v201
	v_add_f32_e32 v113, v145, v201
	v_add_f32_e32 v98, v130, v201
	v_add_f32_e32 v114, v146, v201
	s_waitcnt lgkmcnt(2)
	v_mfma_f32_32x32x16_bf16 v[32:47], v[100:103], v[104:107], v[32:47]
	ds_read_b128 v[124:127], v200 offset:16416
	v_max_f32_e32 v101, v96, v97
	v_max3_f32 v102, v112, v113, v114
	v_add_f32_e32 v99, v131, v201
	v_add_f32_e32 v115, v147, v201
	v_add_f32_e32 v100, v132, v201
	v_add_f32_e32 v116, v148, v201
	s_waitcnt lgkmcnt(2)
	v_mfma_f32_32x32x16_bf16 v[16:31], v[108:111], v[104:107], v[16:31]
	ds_read_b128 v[108:111], v200 offset:21024
	v_max3_f32 v103, v101, v98, v99
	v_max3_f32 v119, v102, v115, v116
	v_add_f32_e32 v101, v133, v201
	v_add_f32_e32 v117, v149, v201
	v_add_f32_e32 v102, v134, v201
	v_add_f32_e32 v118, v150, v201
	s_waitcnt lgkmcnt(2)
	v_mfma_f32_32x32x16_bf16 v[0:15], v[120:123], v[104:107], v[0:15]
	ds_read_b128 v[128:131], v200 offset:25632
	v_max3_f32 v105, v103, v100, v101
	v_max3_f32 v106, v119, v117, v118
	v_add_f32_e32 v103, v135, v201
	v_add_f32_e32 v119, v151, v201
	v_add_f32_e32 v104, v136, v201
	v_add_f32_e32 v120, v152, v201
	s_waitcnt lgkmcnt(2)
	v_mfma_f32_32x32x16_bf16 v[48:63], v[124:127], v[196:199], v[48:63]
	ds_read_b128 v[132:135], v200 offset:30240
	v_max3_f32 v107, v105, v102, v103
	v_max3_f32 v123, v106, v119, v120
	v_add_f32_e32 v105, v137, v201
	v_add_f32_e32 v121, v153, v201
	v_add_f32_e32 v106, v138, v201
	v_add_f32_e32 v122, v154, v201
	s_waitcnt lgkmcnt(2)
	v_mfma_f32_32x32x16_bf16 v[32:47], v[108:111], v[196:199], v[32:47]
	ds_read_b128 v[144:147], v200 offset:16448
	v_max3_f32 v109, v107, v104, v105
	v_max3_f32 v110, v123, v121, v122
	v_add_f32_e32 v107, v139, v201
	v_add_f32_e32 v123, v155, v201
	v_add_f32_e32 v108, v140, v201
	v_add_f32_e32 v124, v156, v201
	s_waitcnt lgkmcnt(2)
	v_mfma_f32_32x32x16_bf16 v[16:31], v[128:131], v[196:199], v[16:31]
	ds_read_b128 v[128:131], v200 offset:21056
	v_max3_f32 v111, v109, v106, v107
	v_max3_f32 v127, v110, v123, v124
	v_add_f32_e32 v109, v141, v201
	v_add_f32_e32 v125, v157, v201
	v_add_f32_e32 v110, v142, v201
	v_add_f32_e32 v126, v158, v201
	s_waitcnt lgkmcnt(2)
	v_mfma_f32_32x32x16_bf16 v[0:15], v[132:135], v[196:199], v[0:15]
	ds_read_b128 v[132:135], v200 offset:25664
	v_max3_f32 v136, v111, v108, v109
	v_max3_f32 v137, v127, v125, v126
	v_add_f32_e32 v111, v143, v201
	v_add_f32_e32 v127, v159, v201
	s_nop 0
	v_max3_f32 v136, v136, v110, v111
	v_max3_f32 v136, v136, v127, v137
	v_mov_b32_e32 v137, v136
	s_nop 1
	v_permlane32_swap_b32 v136, v137
	s_nop 1
	s_nop 0
	v_max_f32_e32 v136, v136, v137
	s_andn2_b64 vcc, exec, s[20:21]
	s_cbranch_vccnz .LBB0_440
	v_cmp_lt_f32_e32 vcc, s39, v136
	s_cmp_lg_u64 vcc, 0
	s_mov_b32 s12, 0
	s_cselect_b64 s[14:15], -1, 0
	v_mov_b32_e32 v137, v211
	s_andn2_b64 vcc, exec, s[14:15]
	s_cbranch_vccz .LBB0_441

.LBB0_448:
	s_andn2_b64 vcc, exec, s[22:23]
	s_cbranch_vccnz .LBB0_450
	v_mov_b32_e32 v128, s13
	s_waitcnt lgkmcnt(0)
	ds_read_b32 v188, v128
	s_mov_b64 s[14:15], -1

; #define FLAS __attribute__((address_space(3)))
; #define FA_SB() __builtin_amdgcn_sched_barrier(0)
; #define FA_EXP2(J, PX, R) do { const float e0_ = __builtin_amdgcn_exp2f(PX[R]), e1_ = __builtin_amdgcn_exp2f(PX[(R) + 1]); ps += e0_; ps += e1_; PWN[(J) >> 2][(J) & 3] = cvtpk(e0_, e1_); } while (0)
; __device__ __forceinline__ void attn_unit_a(FLAS unsigned char* lds, const Unit u) {
;     ...
;         if (ziN) { pN0 = __builtin_amdgcn_mfma_f32_32x32x16_bf16(kf[0], qr[0], z16, 0, 0, 0); FA_EXP2(8, pC1, 0); FA_SB(); pN1 = __builtin_amdgcn_mfma_f32_32x32x16_bf16(kf[1], qr[0], z16, 0, 0, 0); }
;         else { pN0 = __builtin_amdgcn_mfma_f32_32x32x16_bf16(kf[0], qr[0], pN0, 0, 0, 0); FA_EXP2(8, pC1, 0); FA_SB(); pN1 = __builtin_amdgcn_mfma_f32_32x32x16_bf16(kf[1], qr[0], pN1, 0, 0, 0); }
;         kf[0] = FA_KF(2, 0); kf[1] = FA_KF(2, 1); FA_EXP2(9, pC1, 2); FA_SB();
;         pN0 = __builtin_amdgcn_mfma_f32_32x32x16_bf16(kf[2], qr[1], pN0, 0, 0, 0); FA_EXP2(10, pC1, 4); FA_SB();
;         pN1 = __builtin_amdgcn_mfma_f32_32x32x16_bf16(kf[3], qr[1], pN1, 0, 0, 0); kf[2] = FA_KF(3, 0); kf[3] = FA_KF(3, 1); FA_EXP2(11, pC1, 6); FA_SB();
;         pN0 = __builtin_amdgcn_mfma_f32_32x32x16_bf16(kf[0], qr[2], pN0, 0, 0, 0); FA_EXP2(12, pC1, 8); FA_SB();
;         pN1 = __builtin_amdgcn_mfma_f32_32x32x16_bf16(kf[1], qr[2], pN1, 0, 0, 0); FA_EXP2(13, pC1, 10); FA_SB();
;         pN0 = __builtin_amdgcn_mfma_f32_32x32x16_bf16(kf[2], qr[3], pN0, 0, 0, 0); FA_EXP2(14, pC1, 12); FA_SB();
;         pN1 = __builtin_amdgcn_mfma_f32_32x32x16_bf16(kf[3], qr[3], pN1, 0, 0, 0); FA_EXP2(15, pC1, 14); FA_SB();
;     ...
;         lsum += ps; cbC = cbN;
;         if (i + 2 < NT) { *(FLAS u32x4*)(lds + LA_K + (i & 1) * KBUF + kdst) = kreg;
; #pragma unroll
;             for (int j = 0; j < 2; ++j) { *(FLAS u32x2*)(lds + LA_V + ((i + 2) & 3) * VBUF + vdst + j * 64 * VPITCH) = (u32x2){vreg[j].x, vreg[j].y}; *(FLAS u32x2*)(lds + LA_V + ((i + 2) & 3) * VBUF + vdst + j * 64 * VPITCH + 16) = (u32x2){vreg[j].z, vreg[j].w}; } }
.LBB0_452:
	s_andn2_b64 vcc, exec, s[14:15]
	s_cbranch_vccnz .LBB0_454
	v_mfma_f32_32x32x16_bf16 v[128:143], v[204:207], v[160:163], 0
	v_exp_f32_e32 v112, v112
	v_exp_f32_e32 v113, v113
	v_add_f32_e32 v95, v110, v95
	v_add_f32_e32 v95, v111, v95
	v_mfma_f32_32x32x16_bf16 v[144:159], v[200:203], v[160:163], 0
	v_exp_f32_e32 v114, v114
	v_exp_f32_e32 v115, v115
	v_add_f32_e32 v95, v112, v95
	v_add_f32_e32 v95, v113, v95
.LBB0_454:
	ds_read_b128 v[64:67], v249 offset:8192
	ds_read_b128 v[68:71], v249 offset:8704
	s_add_i32 s34, s19, 2
	v_mfma_f32_32x32x16_bf16 v[128:143], v[196:199], v[164:167], v[128:143]
	v_exp_f32_e32 v116, v116
	v_exp_f32_e32 v117, v117
	v_add_f32_e32 v95, v114, v95
	v_add_f32_e32 v95, v115, v95
	v_mfma_f32_32x32x16_bf16 v[144:159], v[192:195], v[164:167], v[144:159]
	ds_read_b128 v[72:75], v250 offset:8192
	ds_read_b128 v[76:79], v250 offset:8704
	v_exp_f32_e32 v118, v118
	v_exp_f32_e32 v119, v119
	v_add_f32_e32 v95, v116, v95
	v_add_f32_e32 v95, v117, v95
	s_waitcnt lgkmcnt(3)
	v_mfma_f32_32x32x16_bf16 v[128:143], v[64:67], v[168:171], v[128:143]
	v_exp_f32_e32 v120, v120
	v_exp_f32_e32 v121, v121
	v_add_f32_e32 v95, v118, v95
	v_add_f32_e32 v95, v119, v95
	s_waitcnt lgkmcnt(2)
	v_mfma_f32_32x32x16_bf16 v[144:159], v[68:71], v[168:171], v[144:159]
	v_exp_f32_e32 v122, v122
	v_exp_f32_e32 v123, v123
	v_add_f32_e32 v95, v120, v95
	v_add_f32_e32 v95, v121, v95
	s_waitcnt lgkmcnt(1)
	v_mfma_f32_32x32x16_bf16 v[128:143], v[72:75], v[172:175], v[128:143]
	v_exp_f32_e32 v124, v124
	v_exp_f32_e32 v125, v125
	v_add_f32_e32 v95, v122, v95
	v_add_f32_e32 v95, v123, v95
	s_waitcnt lgkmcnt(0)
	v_mfma_f32_32x32x16_bf16 v[144:159], v[76:79], v[172:175], v[144:159]
	v_exp_f32_e32 v126, v126
	v_exp_f32_e32 v127, v127
	v_add_f32_e32 v95, v124, v95
	v_add_f32_e32 v95, v125, v95
	v_add_f32_e32 v95, v126, v95
	v_add_f32_e32 v95, v127, v95
	s_andn2_b64 vcc, exec, s[0:1]
	s_cbranch_vccnz .LBB0_456
	s_and_b32 s0, s34, 2
	s_mulk_i32 s0, 0x4800
	v_add_u32_e32 v64, s0, v245
	v_add_u32_e32 v65, 0x4000, v64
	v_add_u32_e32 v64, 0x6000, v64
	s_waitcnt vmcnt(2)
	ds_write_b128 v225, v[176:179]
	s_waitcnt vmcnt(1)
	ds_write2_b64 v65, v[180:181], v[182:183] offset1:2
	s_waitcnt vmcnt(0)
	ds_write2_b64 v64, v[184:185], v[186:187] offset0:128 offset1:130

; #define FLAS __attribute__((address_space(3)))
; __device__ __forceinline__ void attn_unit_a(FLAS unsigned char* lds, const Unit u) {
;     ...
;         const int vsp = (i == 0) ? 0 : ((i - 1) & 3);
;         const FLAS unsigned char* vb_ = lds + LA_V + vsp * VBUF + r32 * VPITCH + hi * 16;
;         const FLAS unsigned char* kb = lds + LA_K + ((i + 1) & 1) * KBUF;
;     ...
;         u32x4 vr[3];
; #pragma unroll
;         for (int m = 0; m < 3; ++m) vr[m] = FA_VFRAG(m);
;         const float off = cbC - mrun;
;         FA_SB();
;         float ra, rb, rm;
;         FA_PVM(0); pC0[0] = fadd_s(pC0[0], off); pC1[0] = fadd_s(pC1[0], off); pC0[1] = fadd_s(pC0[1], off); pC1[1] = fadd_s(pC1[1], off); pC0[2] = fadd_s(pC0[2], off); pC1[2] = fadd_s(pC1[2], off); FA_SB();
;         FA_PVM(1); ra = __builtin_fmaxf(__builtin_fmaxf(pC0[0], pC0[1]), pC0[2]); rb = __builtin_fmaxf(__builtin_fmaxf(pC1[0], pC1[1]), pC1[2]); pC0[3] = fadd_s(pC0[3], off); pC1[3] = fadd_s(pC1[3], off); pC0[4] = fadd_s(pC0[4], off); pC1[4] = fadd_s(pC1[4], off); FA_SB();
;         FA_PVM(2); ra = __builtin_fmaxf(__builtin_fmaxf(ra, pC0[3]), pC0[4]); rb = __builtin_fmaxf(__builtin_fmaxf(rb, pC1[3]), pC1[4]); pC0[5] = fadd_s(pC0[5], off); pC1[5] = fadd_s(pC1[5], off); pC0[6] = fadd_s(pC0[6], off); pC1[6] = fadd_s(pC1[6], off); FA_SB();
;         FA_PVM(3); ra = __builtin_fmaxf(__builtin_fmaxf(ra, pC0[5]), pC0[6]); rb = __builtin_fmaxf(__builtin_fmaxf(rb, pC1[5]), pC1[6]); pC0[7] = fadd_s(pC0[7], off); pC1[7] = fadd_s(pC1[7], off); pC0[8] = fadd_s(pC0[8], off); pC1[8] = fadd_s(pC1[8], off); FA_SB();
;         FA_PVM(4); ra = __builtin_fmaxf(__builtin_fmaxf(ra, pC0[7]), pC0[8]); rb = __builtin_fmaxf(__builtin_fmaxf(rb, pC1[7]), pC1[8]); pC0[9] = fadd_s(pC0[9], off); pC1[9] = fadd_s(pC1[9], off); pC0[10] = fadd_s(pC0[10], off); pC1[10] = fadd_s(pC1[10], off); FA_SB();
;         FA_PVM(5); ra = __builtin_fmaxf(__builtin_fmaxf(ra, pC0[9]), pC0[10]); rb = __builtin_fmaxf(__builtin_fmaxf(rb, pC1[9]), pC1[10]); pC0[11] = fadd_s(pC0[11], off); pC1[11] = fadd_s(pC1[11], off); pC0[12] = fadd_s(pC0[12], off); pC1[12] = fadd_s(pC1[12], off); FA_SB();
;         FA_PVM(6); ra = __builtin_fmaxf(__builtin_fmaxf(ra, pC0[11]), pC0[12]); rb = __builtin_fmaxf(__builtin_fmaxf(rb, pC1[11]), pC1[12]); pC0[13] = fadd_s(pC0[13], off); pC1[13] = fadd_s(pC1[13], off); pC0[14] = fadd_s(pC0[14], off); pC1[14] = fadd_s(pC1[14], off); FA_SB();
.LBB0_460:
	s_and_b32 s0, s19, 2
	s_mulk_i32 s0, 0x4800
	v_add_u32_e32 v201, s0, v251
	v_add_f32_e32 v205, v212, v95
	v_cvt_pk_bf16_f32 v72, v96, v97
	v_cvt_pk_bf16_f32 v73, v98, v99
	v_cvt_pk_bf16_f32 v74, v100, v101
	v_cvt_pk_bf16_f32 v75, v102, v103
	v_cvt_pk_bf16_f32 v232, v104, v105
	v_cvt_pk_bf16_f32 v233, v106, v107
	ds_read_b128 v[64:67], v201 offset:16384
	ds_read_b128 v[68:71], v201 offset:20992
	ds_read_b128 v[76:79], v201 offset:25600
	v_cvt_pk_bf16_f32 v234, v108, v109
	v_cvt_pk_bf16_f32 v235, v110, v111
	v_sub_f32_e32 v188, v188, v211
	s_waitcnt lgkmcnt(2)
	v_mfma_f32_32x32x16_bf16 v[48:63], v[64:67], v[72:75], v[48:63]
	ds_read_b128 v[88:91], v201 offset:30208
	v_add_f32_e32 v64, v128, v188
	v_add_f32_e32 v80, v144, v188
	v_add_f32_e32 v65, v129, v188
	v_add_f32_e32 v81, v145, v188
	v_add_f32_e32 v66, v130, v188
	v_add_f32_e32 v82, v146, v188
	s_waitcnt lgkmcnt(2)
	v_mfma_f32_32x32x16_bf16 v[32:47], v[68:71], v[72:75], v[32:47]
	ds_read_b128 v[92:95], v201 offset:16416
	v_max_f32_e32 v69, v64, v65
	v_max3_f32 v70, v80, v81, v82
	v_add_f32_e32 v67, v131, v188
	v_add_f32_e32 v83, v147, v188
	v_add_f32_e32 v68, v132, v188
	v_add_f32_e32 v84, v148, v188
	s_waitcnt lgkmcnt(2)
	v_mfma_f32_32x32x16_bf16 v[16:31], v[76:79], v[72:75], v[16:31]
	ds_read_b128 v[76:79], v201 offset:21024
	v_max3_f32 v71, v69, v66, v67
	v_max3_f32 v87, v70, v83, v84
	v_add_f32_e32 v69, v133, v188
	v_add_f32_e32 v85, v149, v188
	v_add_f32_e32 v70, v134, v188
	v_add_f32_e32 v86, v150, v188
	s_waitcnt lgkmcnt(2)
	v_mfma_f32_32x32x16_bf16 v[0:15], v[88:91], v[72:75], v[0:15]
	ds_read_b128 v[144:147], v201 offset:25632
	v_max3_f32 v73, v71, v68, v69
	v_max3_f32 v74, v87, v85, v86
	v_add_f32_e32 v71, v135, v188
	v_add_f32_e32 v87, v151, v188
	v_add_f32_e32 v72, v136, v188
	v_add_f32_e32 v88, v152, v188
	s_waitcnt lgkmcnt(2)
	v_mfma_f32_32x32x16_bf16 v[48:63], v[92:95], v[232:235], v[48:63]
	ds_read_b128 v[148:151], v201 offset:30240
	v_max3_f32 v75, v73, v70, v71
	v_max3_f32 v91, v74, v87, v88
	v_add_f32_e32 v73, v137, v188
	v_add_f32_e32 v89, v153, v188
	v_add_f32_e32 v74, v138, v188
	v_add_f32_e32 v90, v154, v188
	s_waitcnt lgkmcnt(2)
	v_mfma_f32_32x32x16_bf16 v[32:47], v[76:79], v[232:235], v[32:47]
	ds_read_b128 v[128:131], v201 offset:16448
	v_max3_f32 v77, v75, v72, v73
	v_max3_f32 v78, v91, v89, v90
	v_add_f32_e32 v75, v139, v188
	v_add_f32_e32 v91, v155, v188
	v_add_f32_e32 v76, v140, v188
	v_add_f32_e32 v92, v156, v188
	s_waitcnt lgkmcnt(2)
	v_mfma_f32_32x32x16_bf16 v[16:31], v[144:147], v[232:235], v[16:31]
	ds_read_b128 v[132:135], v201 offset:21056
	v_max3_f32 v79, v77, v74, v75
	v_max3_f32 v95, v78, v91, v92
	v_add_f32_e32 v77, v141, v188
	v_add_f32_e32 v93, v157, v188
	v_add_f32_e32 v78, v142, v188
	v_add_f32_e32 v94, v158, v188
	s_waitcnt lgkmcnt(2)
	v_mfma_f32_32x32x16_bf16 v[0:15], v[148:151], v[232:235], v[0:15]
	ds_read_b128 v[136:139], v201 offset:25664
	v_max3_f32 v140, v79, v76, v77
	v_max3_f32 v141, v95, v93, v94
	v_add_f32_e32 v79, v143, v188
	v_add_f32_e32 v95, v159, v188
	s_nop 0
	v_max3_f32 v140, v140, v78, v79
	v_max3_f32 v140, v140, v95, v141
	v_mov_b32_e32 v141, v140
	s_nop 1
	v_permlane32_swap_b32 v140, v141
	s_nop 1
	s_nop 0
	v_max_f32_e32 v140, v140, v141
	v_cmp_lt_f32_e32 vcc, s39, v140
	s_cmp_lg_u64 vcc, 0
	s_cselect_b64 s[0:1], -1, 0
	s_cbranch_vccz .LBB0_462
	v_max_f32_e32 v140, v140, v140
	v_max_f32_e32 v140, 0, v140
	v_exp_f32_e64 v226, -v140
	v_add_f32_e32 v211, v211, v140
	v_sub_f32_e32 v64, v64, v140
	v_sub_f32_e32 v65, v65, v140
	v_mul_f32_e32 v205, v205, v226
	v_sub_f32_e32 v66, v66, v140
	v_sub_f32_e32 v67, v67, v140
	v_sub_f32_e32 v68, v68, v140
	v_sub_f32_e32 v69, v69, v140
	v_sub_f32_e32 v70, v70, v140
	v_sub_f32_e32 v71, v71, v140
	v_sub_f32_e32 v72, v72, v140
	v_sub_f32_e32 v73, v73, v140
	v_sub_f32_e32 v74, v74, v140
	v_sub_f32_e32 v75, v75, v140
	v_sub_f32_e32 v76, v76, v140
	v_sub_f32_e32 v77, v77, v140
	v_sub_f32_e32 v78, v78, v140
	v_sub_f32_e32 v79, v79, v140
	v_sub_f32_e32 v80, v80, v140
	v_sub_f32_e32 v81, v81, v140
	v_sub_f32_e32 v82, v82, v140
	v_sub_f32_e32 v83, v83, v140
	v_sub_f32_e32 v84, v84, v140
	v_sub_f32_e32 v85, v85, v140
	v_sub_f32_e32 v86, v86, v140
	v_sub_f32_e32 v87, v87, v140
	v_sub_f32_e32 v88, v88, v140
	v_sub_f32_e32 v89, v89, v140
	v_sub_f32_e32 v90, v90, v140
	v_sub_f32_e32 v91, v91, v140
	v_sub_f32_e32 v92, v92, v140
	v_sub_f32_e32 v93, v93, v140
	v_sub_f32_e32 v94, v94, v140
	v_sub_f32_e32 v95, v95, v140

.LBB0_468:
	s_andn2_b64 vcc, exec, s[22:23]
	s_cbranch_vccnz .LBB0_470
	v_mov_b32_e32 v128, s13
	s_waitcnt lgkmcnt(0)
	ds_read_b32 v204, v128
	s_mov_b64 s[14:15], -1

; #define FLAS __attribute__((address_space(3)))
; #define FA_SB() __builtin_amdgcn_sched_barrier(0)
; #define FA_EXP2(J, PX, R) do { const float e0_ = __builtin_amdgcn_exp2f(PX[R]), e1_ = __builtin_amdgcn_exp2f(PX[(R) + 1]); ps += e0_; ps += e1_; PWN[(J) >> 2][(J) & 3] = cvtpk(e0_, e1_); } while (0)
; __device__ __forceinline__ void attn_unit_a(FLAS unsigned char* lds, const Unit u) {
;     ...
;         if (ziN) { pN0 = __builtin_amdgcn_mfma_f32_32x32x16_bf16(kf[0], qr[0], z16, 0, 0, 0); FA_EXP2(8, pC1, 0); FA_SB(); pN1 = __builtin_amdgcn_mfma_f32_32x32x16_bf16(kf[1], qr[0], z16, 0, 0, 0); }
;         else { pN0 = __builtin_amdgcn_mfma_f32_32x32x16_bf16(kf[0], qr[0], pN0, 0, 0, 0); FA_EXP2(8, pC1, 0); FA_SB(); pN1 = __builtin_amdgcn_mfma_f32_32x32x16_bf16(kf[1], qr[0], pN1, 0, 0, 0); }
;         kf[0] = FA_KF(2, 0); kf[1] = FA_KF(2, 1); FA_EXP2(9, pC1, 2); FA_SB();
;         pN0 = __builtin_amdgcn_mfma_f32_32x32x16_bf16(kf[2], qr[1], pN0, 0, 0, 0); FA_EXP2(10, pC1, 4); FA_SB();
;         pN1 = __builtin_amdgcn_mfma_f32_32x32x16_bf16(kf[3], qr[1], pN1, 0, 0, 0); kf[2] = FA_KF(3, 0); kf[3] = FA_KF(3, 1); FA_EXP2(11, pC1, 6); FA_SB();
;         pN0 = __builtin_amdgcn_mfma_f32_32x32x16_bf16(kf[0], qr[2], pN0, 0, 0, 0); FA_EXP2(12, pC1, 8); FA_SB();
;         pN1 = __builtin_amdgcn_mfma_f32_32x32x16_bf16(kf[1], qr[2], pN1, 0, 0, 0); FA_EXP2(13, pC1, 10); FA_SB();
;         pN0 = __builtin_amdgcn_mfma_f32_32x32x16_bf16(kf[2], qr[3], pN0, 0, 0, 0); FA_EXP2(14, pC1, 12); FA_SB();
;         pN1 = __builtin_amdgcn_mfma_f32_32x32x16_bf16(kf[3], qr[3], pN1, 0, 0, 0); FA_EXP2(15, pC1, 14); FA_SB();
;     ...
;         lsum += ps; cbC = cbN;
;         if (i + 2 < NT) { *(FLAS u32x4*)(lds + LA_K + (i & 1) * KBUF + kdst) = kreg;
; #pragma unroll
;             for (int j = 0; j < 2; ++j) { *(FLAS u32x2*)(lds + LA_V + ((i + 2) & 3) * VBUF + vdst + j * 64 * VPITCH) = (u32x2){vreg[j].x, vreg[j].y}; *(FLAS u32x2*)(lds + LA_V + ((i + 2) & 3) * VBUF + vdst + j * 64 * VPITCH + 16) = (u32x2){vreg[j].z, vreg[j].w}; } }
.LBB0_472:
	s_andn2_b64 vcc, exec, s[14:15]
	s_cbranch_vccnz .LBB0_474
	v_mfma_f32_32x32x16_bf16 v[128:143], v[200:203], v[160:163], 0
	v_exp_f32_e32 v80, v80
	v_exp_f32_e32 v81, v81
	v_add_f32_e32 v127, v78, v127
	v_add_f32_e32 v127, v79, v127
	v_mfma_f32_32x32x16_bf16 v[144:159], v[196:199], v[160:163], 0
	v_exp_f32_e32 v82, v82
	v_exp_f32_e32 v83, v83
	v_add_f32_e32 v127, v80, v127
	v_add_f32_e32 v127, v81, v127
.LBB0_474:
	ds_read_b128 v[96:99], v249
	ds_read_b128 v[100:103], v249 offset:512
	v_mfma_f32_32x32x16_bf16 v[128:143], v[192:195], v[164:167], v[128:143]
	v_exp_f32_e32 v84, v84
	v_exp_f32_e32 v85, v85
	v_add_f32_e32 v127, v82, v127
	v_add_f32_e32 v127, v83, v127
	v_mfma_f32_32x32x16_bf16 v[144:159], v[188:191], v[164:167], v[144:159]
	ds_read_b128 v[104:107], v250
	ds_read_b128 v[108:111], v250 offset:512
	v_exp_f32_e32 v86, v86
	v_exp_f32_e32 v87, v87
	v_add_f32_e32 v127, v84, v127
	v_add_f32_e32 v127, v85, v127
	s_waitcnt lgkmcnt(3)
	v_mfma_f32_32x32x16_bf16 v[128:143], v[96:99], v[168:171], v[128:143]
	v_exp_f32_e32 v88, v88
	v_exp_f32_e32 v89, v89
	v_add_f32_e32 v127, v86, v127
	v_add_f32_e32 v127, v87, v127
	s_waitcnt lgkmcnt(2)
	v_mfma_f32_32x32x16_bf16 v[144:159], v[100:103], v[168:171], v[144:159]
	v_exp_f32_e32 v90, v90
	v_exp_f32_e32 v91, v91
	v_add_f32_e32 v127, v88, v127
	v_add_f32_e32 v127, v89, v127
	s_waitcnt lgkmcnt(1)
	v_mfma_f32_32x32x16_bf16 v[128:143], v[104:107], v[172:175], v[128:143]
	v_exp_f32_e32 v92, v92
	v_exp_f32_e32 v93, v93
	v_add_f32_e32 v127, v90, v127
	v_add_f32_e32 v127, v91, v127
	s_waitcnt lgkmcnt(0)
	v_mfma_f32_32x32x16_bf16 v[144:159], v[108:111], v[172:175], v[144:159]
	v_exp_f32_e32 v94, v94
	v_exp_f32_e32 v95, v95
	v_add_f32_e32 v127, v92, v127
	v_add_f32_e32 v127, v93, v127
	v_add_f32_e32 v127, v94, v127
	v_add_f32_e32 v127, v95, v127
	s_andn2_b64 vcc, exec, s[20:21]
	s_cbranch_vccnz .LBB0_476
	v_add_u32_e32 v96, s18, v245
	v_add_u32_e32 v97, 0x4000, v96
	v_add_u32_e32 v96, 0x6000, v96
	s_waitcnt vmcnt(2)
	ds_write_b128 v225, v[176:179] offset:8192
	s_waitcnt vmcnt(1)
	ds_write2_b64 v97, v[180:181], v[182:183] offset1:2
	s_waitcnt vmcnt(0)
	ds_write2_b64 v96, v[184:185], v[186:187] offset0:128 offset1:130
